# prologue/epilogue de-serialisation: peeled last attention stage issues all 8 QK fragment reads up front
# speedup vs baseline: 1.0034x; 1.0034x over previous
.LBB0_490:
	v_add_u32_e32 v0, v76, v73
	v_add_u32_e32 v100, v76, v70
	s_waitcnt lgkmcnt(0)
	s_barrier
	ds_read_b128 v[26:29], v0 offset:16384
	ds_read_b128 v[30:33], v0 offset:18432
	ds_read_b128 v[36:39], v0 offset:20480
	ds_read_b128 v[40:43], v0 offset:22528
	ds_read_b128 v[104:107], v100 offset:16384
	ds_read_b128 v[108:111], v100 offset:18432
	ds_read_b128 v[112:115], v100 offset:20480
	ds_read_b128 v[100:103], v100 offset:22528
	v_readlane_b32 s89, v255, 12
	v_readlane_b32 s34, v255, 15
	s_waitcnt lgkmcnt(6)
	v_mfma_f32_16x16x32_bf16 v[32:35], v[30:33], v[22:25], 0
	v_add_u32_e32 v30, v76, v70
	v_readlane_b32 s88, v255, 35
	s_mov_b32 s38, s86
	v_mfma_f32_16x16x32_bf16 v[26:29], v[26:29], v[22:25], 0
	s_waitcnt lgkmcnt(5)
	v_mfma_f32_16x16x32_bf16 v[36:39], v[36:39], v[22:25], 0
	s_waitcnt lgkmcnt(4)
	v_mfma_f32_16x16x32_bf16 v[22:25], v[40:43], v[22:25], 0
	s_waitcnt lgkmcnt(3)
	v_mfma_f32_16x16x32_bf16 v[40:43], v[104:107], v[18:21], v[26:29]
	s_waitcnt lgkmcnt(2)
	v_mfma_f32_16x16x32_bf16 v[44:47], v[108:111], v[18:21], v[32:35]
	s_waitcnt lgkmcnt(1)
	v_mfma_f32_16x16x32_bf16 v[36:39], v[112:115], v[18:21], v[36:39]
	s_waitcnt lgkmcnt(0)
	v_mfma_f32_16x16x32_bf16 v[48:51], v[100:103], v[18:21], v[22:25]
	s_nop 15
	s_nop 3
	v_mul_f32_e32 v33, 0x3e38aa3b, v41
	v_mul_f32_e32 v31, 0x3e38aa3b, v44
	v_mul_f32_e32 v34, 0x3e38aa3b, v47
	v_mul_f32_e32 v32, 0x3e38aa3b, v38
	v_mul_f32_e32 v23, 0x3e38aa3b, v40
	v_mul_f32_e32 v29, 0x3e38aa3b, v42
	v_max3_f32 v35, v23, v33, v29
	v_mul_f32_e32 v26, 0x3e38aa3b, v43
	v_max3_f32 v35, v35, v26, v31
	v_mul_f32_e32 v27, 0x3e38aa3b, v45
	v_mul_f32_e32 v24, 0x3e38aa3b, v46
	v_max3_f32 v35, v35, v27, v24
	v_mul_f32_e32 v25, 0x3e38aa3b, v36
	v_max3_f32 v35, v35, v34, v25
	v_mul_f32_e32 v22, 0x3e38aa3b, v37
	v_max3_f32 v35, v35, v22, v32
	v_mul_f32_e32 v28, 0x3e38aa3b, v39
	v_mul_f32_e32 v21, 0x3e38aa3b, v48
	v_max3_f32 v35, v35, v28, v21
	v_mul_f32_e32 v20, 0x3e38aa3b, v49
	v_mul_f32_e32 v19, 0x3e38aa3b, v50
	v_max3_f32 v35, v35, v20, v19
	v_add_f32_e32 v36, 0x41000000, v71
	v_mul_f32_e32 v18, 0x3e38aa3b, v51
	v_max3_f32 v35, v35, v18, v18
	s_nop 0
	v_cmp_gt_f32_e32 vcc, v35, v36
	s_cbranch_vccz .LBB0_492
	ds_swizzle_b32 v36, v35 offset:swizzle(SWAP,16)
	v_max_f32_e32 v35, v35, v35
	s_waitcnt lgkmcnt(0)
	v_max_f32_e32 v36, v36, v36
	v_max_f32_e32 v35, v35, v36
	ds_bpermute_b32 v36, v59, v35
	s_waitcnt lgkmcnt(0)
	v_max3_f32 v35, v71, v35, v36
	v_sub_f32_e32 v36, v71, v35
	v_exp_f32_e32 v36, v36
	v_mov_b32_e32 v71, v35
	v_mul_f32_e32 v68, v68, v36
	v_pk_mul_f32 v[16:17], v[16:17], v[36:37] op_sel_hi:[1,0]
	v_pk_mul_f32 v[14:15], v[14:15], v[36:37] op_sel_hi:[1,0]
	v_pk_mul_f32 v[12:13], v[12:13], v[36:37] op_sel_hi:[1,0]
	v_pk_mul_f32 v[10:11], v[10:11], v[36:37] op_sel_hi:[1,0]
	v_pk_mul_f32 v[8:9], v[8:9], v[36:37] op_sel_hi:[1,0]
	v_pk_mul_f32 v[6:7], v[6:7], v[36:37] op_sel_hi:[1,0]
	v_pk_mul_f32 v[4:5], v[4:5], v[36:37] op_sel_hi:[1,0]
	v_pk_mul_f32 v[2:3], v[2:3], v[36:37] op_sel_hi:[1,0]
